# adds f32->bf16 copy loops with 8 loads in flight (256-WG fast path) and straight-line rhs build in gdn_prep
# speedup vs baseline: 1.0369x; 1.0106x over previous
; DI unsigned pk2(float lo, float hi) { typedef __bf16 b2 __attribute__((ext_vector_type(2))); f32x2 v = {lo, hi}; b2 b = __builtin_convertvector(v, b2); return __builtin_bit_cast(unsigned, b); }
; DI void cvt_phase(const Ctx& c, const float* src, bf16_t* dst, float* copy, size_t n) {
;     const size_t n4 = n / 4, stride = (size_t)c.G * 512;
;     for (size_t i = (size_t)c.bid * 512 + c.tid; i < n4; i += stride) { const f32x4 v = ((const f32x4*)src)[i]; u32x2 w; w.x = pk2(v[0], v[1]); w.y = pk2(v[2], v[3]); ((u32x2*)dst)[i] = w; if (copy) ((f32x4*)copy)[i] = v; }
; }
;     unsigned char* ws = args.ws;
;     bf16_t* W = (bf16_t*)(ws + WS_W); bf16_t* AB = (bf16_t*)(ws + WS_AB); bf16_t* HB0 = (bf16_t*)(ws + WS_G); bf16_t* HB1 = (bf16_t*)(ws + WS_HB1);
;     float* H = args.out;
;     const float* ln_g = args.in[17] + (size_t)l * 3 * DM; const float* ln_b = args.in[18] + (size_t)l * 3 * DM;
;     LayerW L; L.a1 = args.in[3] + (size_t)l * 1024 * 5632; L.a2 = args.in[4] + (size_t)l * 2816 * 1024; L.mi = args.in[5] + (size_t)l * 1024 * NIN; L.uq = args.in[12] + (size_t)l * 256 * 384;
;     L.ukv = args.in[13] + (size_t)l * 128 * 512; L.wo = args.in[14] + (size_t)l * 1024 * 1024; L.b1 = args.in[15] + (size_t)l * 1024 * 5632; L.b2 = args.in[16] + (size_t)l * 2816 * 1024;
;     L.gt = args.in[19] + (size_t)l * 1024 * 1024; L.pp = args.in[20] + (size_t)l * 256 * 1024;
;     if constexpr (SP == 0) {
;         if (l == 0) { cvt_phase(c, args.in[0], HB0, nullptr, (size_t)T_ * DM); rope_phase(c, (const int*)args.in[2], (f32x2*)(ws + WS_ROPE)); }
.LBB0_17:
	s_load_dwordx16 s[4:19], s[0:1], 0x40
	s_lshr_b32 s0, s83, 6
	s_cmp_lt_i32 s92, 2
	v_and_b32_e32 v202, 63, v152
	s_waitcnt lgkmcnt(0)
	v_writelane_b32 v247, s4, 9
	s_nop 1
	v_writelane_b32 v247, s5, 10
	v_writelane_b32 v247, s6, 11
	v_writelane_b32 v247, s7, 12
	v_writelane_b32 v247, s8, 13
	v_writelane_b32 v247, s9, 14
	v_writelane_b32 v247, s10, 15
	v_writelane_b32 v247, s11, 16
	v_writelane_b32 v247, s12, 17
	v_writelane_b32 v247, s13, 18
	v_writelane_b32 v247, s14, 19
	v_writelane_b32 v247, s15, 20
	v_writelane_b32 v247, s16, 21
	v_writelane_b32 v247, s17, 22
	v_writelane_b32 v247, s18, 23
	v_writelane_b32 v247, s19, 24
	s_cselect_b64 s[4:5], -1, 0
	s_cmp_gt_i32 s93, 1
	v_writelane_b32 v247, s0, 25
	s_cselect_b64 s[0:1], -1, 0
	s_and_b64 s[0:1], s[4:5], s[0:1]
	s_andn2_b64 vcc, exec, s[0:1]
	s_cbranch_vccnz .LBB0_31
	s_ashr_i32 s71, s70, 31
	s_lshl_b64 s[0:1], s[70:71], 9
	v_mov_b32_e32 v153, 0
	v_lshl_add_u64 v[2:3], s[0:1], 0, v[152:153]
	s_mov_b64 s[0:1], 0x400000
	v_cmp_gt_u64_e32 vcc, s[0:1], v[2:3]
	s_and_saveexec_b64 s[0:1], vcc
	s_cbranch_execz .LBB0_21
	s_ashr_i32 s9, s30, 31
	s_mov_b32 s8, s30
	s_lshl_b64 s[2:3], s[8:9], 9
	s_lshl_b64 s[6:7], s[70:71], 13
	s_add_u32 s6, s36, s6
	v_lshlrev_b32_e32 v4, 4, v152
	v_mov_b32_e32 v5, v153
	s_addc_u32 s7, s37, s7
	v_lshl_add_u64 v[4:5], s[6:7], 0, v[4:5]
	s_lshl_b64 s[6:7], s[8:9], 13
	s_lshl_b64 s[10:11], s[70:71], 12
	s_add_u32 s10, s34, s10
	v_lshlrev_b32_e32 v6, 3, v152
	v_mov_b32_e32 v7, v153
	s_addc_u32 s11, s35, s11
	v_lshl_add_u64 v[6:7], s[10:11], 0, v[6:7]
	s_mov_b64 s[10:11], 0x9800000
	v_lshl_add_u64 v[6:7], v[6:7], 0, s[10:11]
	s_lshl_b64 s[8:9], s[8:9], 12
	s_mov_b64 s[10:11], 0
	s_mov_b64 s[12:13], 0x3fffff
	s_cmp_lg_u32 s2, 0x20000
	s_cbranch_scc1 .LBB0_20
	s_movk_i32 s101, 4
.Lcvt_fast_0:
	global_load_dwordx4 v[8:11], v[4:5], off
	v_lshl_add_u64 v[4:5], v[4:5], 0, s[6:7]
	global_load_dwordx4 v[12:15], v[4:5], off
	v_lshl_add_u64 v[4:5], v[4:5], 0, s[6:7]
	global_load_dwordx4 v[16:19], v[4:5], off
	v_lshl_add_u64 v[4:5], v[4:5], 0, s[6:7]
	global_load_dwordx4 v[20:23], v[4:5], off
	v_lshl_add_u64 v[4:5], v[4:5], 0, s[6:7]
	global_load_dwordx4 v[24:27], v[4:5], off
	v_lshl_add_u64 v[4:5], v[4:5], 0, s[6:7]
	global_load_dwordx4 v[28:31], v[4:5], off
	v_lshl_add_u64 v[4:5], v[4:5], 0, s[6:7]
	global_load_dwordx4 v[32:35], v[4:5], off
	v_lshl_add_u64 v[4:5], v[4:5], 0, s[6:7]
	global_load_dwordx4 v[36:39], v[4:5], off
	v_lshl_add_u64 v[4:5], v[4:5], 0, s[6:7]
	s_waitcnt vmcnt(7)
	v_cvt_pk_bf16_f32 v8, v8, v9
	v_cvt_pk_bf16_f32 v9, v10, v11
	global_store_dwordx2 v[6:7], v[8:9], off
	v_lshl_add_u64 v[6:7], v[6:7], 0, s[8:9]
	s_waitcnt vmcnt(7)
	v_cvt_pk_bf16_f32 v12, v12, v13
	v_cvt_pk_bf16_f32 v13, v14, v15
	global_store_dwordx2 v[6:7], v[12:13], off
	v_lshl_add_u64 v[6:7], v[6:7], 0, s[8:9]
	s_waitcnt vmcnt(7)
	v_cvt_pk_bf16_f32 v16, v16, v17
	v_cvt_pk_bf16_f32 v17, v18, v19
	global_store_dwordx2 v[6:7], v[16:17], off
	v_lshl_add_u64 v[6:7], v[6:7], 0, s[8:9]
	s_waitcnt vmcnt(7)
	v_cvt_pk_bf16_f32 v20, v20, v21
	v_cvt_pk_bf16_f32 v21, v22, v23
	global_store_dwordx2 v[6:7], v[20:21], off
	v_lshl_add_u64 v[6:7], v[6:7], 0, s[8:9]
	s_waitcnt vmcnt(7)
	v_cvt_pk_bf16_f32 v24, v24, v25
	v_cvt_pk_bf16_f32 v25, v26, v27
	global_store_dwordx2 v[6:7], v[24:25], off
	v_lshl_add_u64 v[6:7], v[6:7], 0, s[8:9]
	s_waitcnt vmcnt(7)
	v_cvt_pk_bf16_f32 v28, v28, v29
	v_cvt_pk_bf16_f32 v29, v30, v31
	global_store_dwordx2 v[6:7], v[28:29], off
	v_lshl_add_u64 v[6:7], v[6:7], 0, s[8:9]
	s_waitcnt vmcnt(7)
	v_cvt_pk_bf16_f32 v32, v32, v33
	v_cvt_pk_bf16_f32 v33, v34, v35
	global_store_dwordx2 v[6:7], v[32:33], off
	v_lshl_add_u64 v[6:7], v[6:7], 0, s[8:9]
	s_waitcnt vmcnt(7)
	v_cvt_pk_bf16_f32 v36, v36, v37
	v_cvt_pk_bf16_f32 v37, v38, v39
	global_store_dwordx2 v[6:7], v[36:37], off
	v_lshl_add_u64 v[6:7], v[6:7], 0, s[8:9]
	s_sub_u32 s101, s101, 1
	s_cmp_lg_u32 s101, 0
	s_cbranch_scc1 .Lcvt_fast_0
	s_branch .LBB0_21

; DI float fexp2(float x) { return __builtin_amdgcn_exp2f(x); }
;     ...
;     for (int e = tid; e < 8192; e += 512) { const int i = e >> 7, cc = e & 127; const float bi = bet[i];
;         rhs[i * 132 + cc] = cc < 64 ? vc[i * 68 + cc] * bi : kc[i * 68 + cc - 64] * bi * fexp2(gcs[i] * 1.4426950408889634f); }
.LBB0_511:
	v_lshrrev_b32_e32 v2, 7, v152
	v_lshlrev_b32_e32 v3, 2, v2
	v_mad_u32_u24 v4, v2, s75, v174
	v_mad_u32_u24 v5, v2, s76, v175
	v_add_u32_e32 v3, 0x19600, v3
	v_add_u32_e32 v6, 0xffffff00, v3
	v_add_u32_e32 v4, 0x100, v4
	v_add_u32_e32 v5, 0x100, v5
	ds_read_b32 v8, v3 offset:0
	ds_read_b32 v9, v3 offset:16
	ds_read_b32 v10, v3 offset:32
	ds_read_b32 v11, v3 offset:48
	ds_read_b32 v12, v3 offset:64
	ds_read_b32 v13, v3 offset:80
	ds_read_b32 v14, v3 offset:96
	ds_read_b32 v15, v3 offset:112
	ds_read_b32 v16, v3 offset:128
	ds_read_b32 v17, v3 offset:144
	ds_read_b32 v18, v3 offset:160
	ds_read_b32 v19, v3 offset:176
	ds_read_b32 v20, v3 offset:192
	ds_read_b32 v21, v3 offset:208
	ds_read_b32 v22, v3 offset:224
	ds_read_b32 v23, v3 offset:240
	s_mov_b64 s[52:53], exec
	s_and_b64 exec, s[52:53], s[80:81]
	s_cbranch_execz .Lrhs_v_0
	ds_read_b32 v204, v6 offset:0
	ds_read_b32 v205, v6 offset:16
	ds_read_b32 v206, v6 offset:32
	ds_read_b32 v207, v6 offset:48
	ds_read_b32 v208, v6 offset:64
	ds_read_b32 v209, v6 offset:80
	ds_read_b32 v210, v6 offset:96
	ds_read_b32 v211, v6 offset:112
	ds_read_b32 v212, v6 offset:128
	ds_read_b32 v213, v6 offset:144
	ds_read_b32 v214, v6 offset:160
	ds_read_b32 v215, v6 offset:176
	ds_read_b32 v216, v6 offset:192
	ds_read_b32 v217, v6 offset:208
	ds_read_b32 v218, v6 offset:224
	ds_read_b32 v219, v6 offset:240
	ds_read_b32 v220, v4 offset:0
	ds_read_b32 v221, v4 offset:1088
	ds_read_b32 v222, v4 offset:2176
	ds_read_b32 v223, v4 offset:3264
	ds_read_b32 v224, v4 offset:4352
	ds_read_b32 v225, v4 offset:5440
	ds_read_b32 v226, v4 offset:6528
	ds_read_b32 v227, v4 offset:7616
	ds_read_b32 v228, v4 offset:8704
	ds_read_b32 v229, v4 offset:9792
	ds_read_b32 v230, v4 offset:10880
	ds_read_b32 v231, v4 offset:11968
	ds_read_b32 v232, v4 offset:13056
	ds_read_b32 v233, v4 offset:14144
	ds_read_b32 v234, v4 offset:15232
	ds_read_b32 v235, v4 offset:16320
	s_waitcnt lgkmcnt(0)
	v_mul_f32_e32 v204, 0x3fb8aa3b, v204
	v_mul_f32_e32 v205, 0x3fb8aa3b, v205
	v_mul_f32_e32 v206, 0x3fb8aa3b, v206
	v_mul_f32_e32 v207, 0x3fb8aa3b, v207
	v_mul_f32_e32 v208, 0x3fb8aa3b, v208
	v_mul_f32_e32 v209, 0x3fb8aa3b, v209
	v_mul_f32_e32 v210, 0x3fb8aa3b, v210
	v_mul_f32_e32 v211, 0x3fb8aa3b, v211
	v_mul_f32_e32 v212, 0x3fb8aa3b, v212
	v_mul_f32_e32 v213, 0x3fb8aa3b, v213
	v_mul_f32_e32 v214, 0x3fb8aa3b, v214
	v_mul_f32_e32 v215, 0x3fb8aa3b, v215
	v_mul_f32_e32 v216, 0x3fb8aa3b, v216
	v_mul_f32_e32 v217, 0x3fb8aa3b, v217
	v_mul_f32_e32 v218, 0x3fb8aa3b, v218
	v_mul_f32_e32 v219, 0x3fb8aa3b, v219
	v_exp_f32_e32 v204, v204
	v_exp_f32_e32 v205, v205
	v_exp_f32_e32 v206, v206
	v_exp_f32_e32 v207, v207
	v_exp_f32_e32 v208, v208
	v_exp_f32_e32 v209, v209
	v_exp_f32_e32 v210, v210
	v_exp_f32_e32 v211, v211
	v_exp_f32_e32 v212, v212
	v_exp_f32_e32 v213, v213
	v_exp_f32_e32 v214, v214
	v_exp_f32_e32 v215, v215
	v_exp_f32_e32 v216, v216
	v_exp_f32_e32 v217, v217
	v_exp_f32_e32 v218, v218
	v_exp_f32_e32 v219, v219
	v_mul_f32_e32 v8, v8, v220
	v_mul_f32_e32 v9, v9, v221
	v_mul_f32_e32 v10, v10, v222
	v_mul_f32_e32 v11, v11, v223
	v_mul_f32_e32 v12, v12, v224
	v_mul_f32_e32 v13, v13, v225
	v_mul_f32_e32 v14, v14, v226
	v_mul_f32_e32 v15, v15, v227
	v_mul_f32_e32 v16, v16, v228
	v_mul_f32_e32 v17, v17, v229
	v_mul_f32_e32 v18, v18, v230
	v_mul_f32_e32 v19, v19, v231
	v_mul_f32_e32 v20, v20, v232
	v_mul_f32_e32 v21, v21, v233
	v_mul_f32_e32 v22, v22, v234
	v_mul_f32_e32 v23, v23, v235
	v_mul_f32_e32 v8, v8, v204
	v_mul_f32_e32 v9, v9, v205
	v_mul_f32_e32 v10, v10, v206
	v_mul_f32_e32 v11, v11, v207
	v_mul_f32_e32 v12, v12, v208
	v_mul_f32_e32 v13, v13, v209
	v_mul_f32_e32 v14, v14, v210
	v_mul_f32_e32 v15, v15, v211
	v_mul_f32_e32 v16, v16, v212
	v_mul_f32_e32 v17, v17, v213
	v_mul_f32_e32 v18, v18, v214
	v_mul_f32_e32 v19, v19, v215
	v_mul_f32_e32 v20, v20, v216
	v_mul_f32_e32 v21, v21, v217
	v_mul_f32_e32 v22, v22, v218
	v_mul_f32_e32 v23, v23, v219
.Lrhs_v_0:
	s_andn2_b64 exec, s[52:53], s[80:81]
	s_cbranch_execz .Lrhs_w_0
	ds_read_b32 v220, v4 offset:17664
	ds_read_b32 v221, v4 offset:18752
	ds_read_b32 v222, v4 offset:19840
	ds_read_b32 v223, v4 offset:20928
	ds_read_b32 v224, v4 offset:22016
	ds_read_b32 v225, v4 offset:23104
	ds_read_b32 v226, v4 offset:24192
	ds_read_b32 v227, v4 offset:25280
	ds_read_b32 v228, v4 offset:26368
	ds_read_b32 v229, v4 offset:27456
	ds_read_b32 v230, v4 offset:28544
	ds_read_b32 v231, v4 offset:29632
	ds_read_b32 v232, v4 offset:30720
	ds_read_b32 v233, v4 offset:31808
	ds_read_b32 v234, v4 offset:32896
	ds_read_b32 v235, v4 offset:33984
	s_waitcnt lgkmcnt(0)
	v_mul_f32_e32 v8, v8, v220
	v_mul_f32_e32 v9, v9, v221
	v_mul_f32_e32 v10, v10, v222
	v_mul_f32_e32 v11, v11, v223
	v_mul_f32_e32 v12, v12, v224
	v_mul_f32_e32 v13, v13, v225
	v_mul_f32_e32 v14, v14, v226
	v_mul_f32_e32 v15, v15, v227
	v_mul_f32_e32 v16, v16, v228
	v_mul_f32_e32 v17, v17, v229
	v_mul_f32_e32 v18, v18, v230
	v_mul_f32_e32 v19, v19, v231
	v_mul_f32_e32 v20, v20, v232
	v_mul_f32_e32 v21, v21, v233
	v_mul_f32_e32 v22, v22, v234
	v_mul_f32_e32 v23, v23, v235
.Lrhs_w_0:
	s_mov_b64 exec, s[52:53]
	ds_write_b32 v5, v8 offset:0
	ds_write_b32 v5, v9 offset:2112
	ds_write_b32 v5, v10 offset:4224
	ds_write_b32 v5, v11 offset:6336
	ds_write_b32 v5, v12 offset:8448
	ds_write_b32 v5, v13 offset:10560
	ds_write_b32 v5, v14 offset:12672
	ds_write_b32 v5, v15 offset:14784
	ds_write_b32 v5, v16 offset:16896
	ds_write_b32 v5, v17 offset:19008
	ds_write_b32 v5, v18 offset:21120
	ds_write_b32 v5, v19 offset:23232
	ds_write_b32 v5, v20 offset:25344
	ds_write_b32 v5, v21 offset:27456
	ds_write_b32 v5, v22 offset:29568
	ds_write_b32 v5, v23 offset:31680
	s_mov_b64 s[42:43], 0
	s_ashr_i32 s3, s2, 31

; DI unsigned pk2(float lo, float hi) { typedef __bf16 b2 __attribute__((ext_vector_type(2))); f32x2 v = {lo, hi}; b2 b = __builtin_convertvector(v, b2); return __builtin_bit_cast(unsigned, b); }
; DI void cvt_phase(const Ctx& c, const float* src, bf16_t* dst, float* copy, size_t n) {
;     const size_t n4 = n / 4, stride = (size_t)c.G * 512;
;     for (size_t i = (size_t)c.bid * 512 + c.tid; i < n4; i += stride) { const f32x4 v = ((const f32x4*)src)[i]; u32x2 w; w.x = pk2(v[0], v[1]); w.y = pk2(v[2], v[3]); ((u32x2*)dst)[i] = w; if (copy) ((f32x4*)copy)[i] = v; }
; }
;     ...
;     else if constexpr (SP == 7) { pg8::Gemm g{AB, W + OW_O, T_, 1024, 1024, NINP}; pg8::StaticOrder S; S.init(T_, 1024, c.G, c.bid);
;         pg8::EpiResidLn E{H, H, HB0, DM, ALPHA, 1.0f, ln_g + DM, ln_b + DM, (unsigned long long*)(ws + WS_CTL + 524288), (unsigned*)(ws + WS_CTL + 131072) + (l * 3 + 1) * 4096};
;         pg8::gemm_phase<pg8::EpiResidLn, pg8::StaticOrder, false>(c.lds, g, S, E);
;         cvt_phase(c, args.in[1] + (size_t)l * T_ * 256, (bf16_t*)(ws + WS_SVT), nullptr, (size_t)T_ * 256); }
.LBB0_1045:
	s_lshl_b64 s[0:1], s[70:71], 9
	v_mov_b32_e32 v153, 0
	v_lshl_add_u64 v[2:3], s[0:1], 0, v[152:153]
	s_mov_b64 s[0:1], 0x100000
	v_cmp_gt_u64_e32 vcc, s[0:1], v[2:3]
	s_and_saveexec_b64 s[0:1], vcc
	s_cbranch_execz .LBB0_1048
	s_lshl_b64 s[4:5], s[2:3], 9
	s_lshl_b64 s[6:7], s[70:71], 13
	s_add_u32 s6, s38, s6
	v_lshlrev_b32_e32 v4, 4, v152
	v_mov_b32_e32 v5, v153
	s_addc_u32 s7, s39, s7
	v_lshl_add_u64 v[4:5], s[6:7], 0, v[4:5]
	s_lshl_b64 s[6:7], s[2:3], 13
	s_lshl_b64 s[8:9], s[70:71], 12
	s_add_u32 s8, s34, s8
	v_lshlrev_b32_e32 v6, 3, v152
	v_mov_b32_e32 v7, v153
	s_addc_u32 s9, s35, s9
	v_lshl_add_u64 v[6:7], s[8:9], 0, v[6:7]
	s_mov_b64 s[8:9], 0x10800000
	v_lshl_add_u64 v[6:7], v[6:7], 0, s[8:9]
	s_lshl_b64 s[2:3], s[2:3], 12
	s_mov_b64 s[8:9], 0
	s_mov_b64 s[10:11], 0xfffff
	s_cmp_lg_u32 s4, 0x20000
	s_cbranch_scc1 .LBB0_1047
	s_movk_i32 s101, 1
.Lcvt_fast_1:
	global_load_dwordx4 v[8:11], v[4:5], off
	v_lshl_add_u64 v[4:5], v[4:5], 0, s[6:7]
	global_load_dwordx4 v[12:15], v[4:5], off
	v_lshl_add_u64 v[4:5], v[4:5], 0, s[6:7]
	global_load_dwordx4 v[16:19], v[4:5], off
	v_lshl_add_u64 v[4:5], v[4:5], 0, s[6:7]
	global_load_dwordx4 v[20:23], v[4:5], off
	v_lshl_add_u64 v[4:5], v[4:5], 0, s[6:7]
	global_load_dwordx4 v[24:27], v[4:5], off
	v_lshl_add_u64 v[4:5], v[4:5], 0, s[6:7]
	global_load_dwordx4 v[28:31], v[4:5], off
	v_lshl_add_u64 v[4:5], v[4:5], 0, s[6:7]
	global_load_dwordx4 v[32:35], v[4:5], off
	v_lshl_add_u64 v[4:5], v[4:5], 0, s[6:7]
	global_load_dwordx4 v[36:39], v[4:5], off
	v_lshl_add_u64 v[4:5], v[4:5], 0, s[6:7]
	s_waitcnt vmcnt(7)
	v_cvt_pk_bf16_f32 v8, v8, v9
	v_cvt_pk_bf16_f32 v9, v10, v11
	global_store_dwordx2 v[6:7], v[8:9], off
	v_lshl_add_u64 v[6:7], v[6:7], 0, s[2:3]
	s_waitcnt vmcnt(7)
	v_cvt_pk_bf16_f32 v12, v12, v13
	v_cvt_pk_bf16_f32 v13, v14, v15
	global_store_dwordx2 v[6:7], v[12:13], off
	v_lshl_add_u64 v[6:7], v[6:7], 0, s[2:3]
	s_waitcnt vmcnt(7)
	v_cvt_pk_bf16_f32 v16, v16, v17
	v_cvt_pk_bf16_f32 v17, v18, v19
	global_store_dwordx2 v[6:7], v[16:17], off
	v_lshl_add_u64 v[6:7], v[6:7], 0, s[2:3]
	s_waitcnt vmcnt(7)
	v_cvt_pk_bf16_f32 v20, v20, v21
	v_cvt_pk_bf16_f32 v21, v22, v23
	global_store_dwordx2 v[6:7], v[20:21], off
	v_lshl_add_u64 v[6:7], v[6:7], 0, s[2:3]
	s_waitcnt vmcnt(7)
	v_cvt_pk_bf16_f32 v24, v24, v25
	v_cvt_pk_bf16_f32 v25, v26, v27
	global_store_dwordx2 v[6:7], v[24:25], off
	v_lshl_add_u64 v[6:7], v[6:7], 0, s[2:3]
	s_waitcnt vmcnt(7)
	v_cvt_pk_bf16_f32 v28, v28, v29
	v_cvt_pk_bf16_f32 v29, v30, v31
	global_store_dwordx2 v[6:7], v[28:29], off
	v_lshl_add_u64 v[6:7], v[6:7], 0, s[2:3]
	s_waitcnt vmcnt(7)
	v_cvt_pk_bf16_f32 v32, v32, v33
	v_cvt_pk_bf16_f32 v33, v34, v35
	global_store_dwordx2 v[6:7], v[32:33], off
	v_lshl_add_u64 v[6:7], v[6:7], 0, s[2:3]
	s_waitcnt vmcnt(7)
	v_cvt_pk_bf16_f32 v36, v36, v37
	v_cvt_pk_bf16_f32 v37, v38, v39
	global_store_dwordx2 v[6:7], v[36:37], off
	v_lshl_add_u64 v[6:7], v[6:7], 0, s[2:3]
	s_sub_u32 s101, s101, 1
	s_cmp_lg_u32 s101, 0
	s_cbranch_scc1 .Lcvt_fast_1
	s_branch .LBB0_1048

; DI float fexp2(float x) { return __builtin_amdgcn_exp2f(x); }
;     ...
;     for (int e = tid; e < 8192; e += 512) { const int i = e >> 7, cc = e & 127; const float bi = bet[i];
;         rhs[i * 132 + cc] = cc < 64 ? vc[i * 68 + cc] * bi : kc[i * 68 + cc - 64] * bi * fexp2(gcs[i] * 1.4426950408889634f); }
.LBB0_1822:
	v_lshrrev_b32_e32 v2, 7, v152
	v_lshlrev_b32_e32 v3, 2, v2
	v_mad_u32_u24 v4, v2, s20, v174
	v_mad_u32_u24 v5, v2, s21, v175
	v_add_u32_e32 v3, 0x19600, v3
	v_add_u32_e32 v6, 0xffffff00, v3
	v_add_u32_e32 v4, 0x100, v4
	v_add_u32_e32 v5, 0x100, v5
	ds_read_b32 v8, v3 offset:0
	ds_read_b32 v9, v3 offset:16
	ds_read_b32 v10, v3 offset:32
	ds_read_b32 v11, v3 offset:48
	ds_read_b32 v12, v3 offset:64
	ds_read_b32 v13, v3 offset:80
	ds_read_b32 v14, v3 offset:96
	ds_read_b32 v15, v3 offset:112
	ds_read_b32 v16, v3 offset:128
	ds_read_b32 v17, v3 offset:144
	ds_read_b32 v18, v3 offset:160
	ds_read_b32 v19, v3 offset:176
	ds_read_b32 v20, v3 offset:192
	ds_read_b32 v21, v3 offset:208
	ds_read_b32 v22, v3 offset:224
	ds_read_b32 v23, v3 offset:240
	s_mov_b64 s[52:53], exec
	s_and_b64 exec, s[52:53], s[80:81]
	s_cbranch_execz .Lrhs_v_1
	ds_read_b32 v204, v6 offset:0
	ds_read_b32 v205, v6 offset:16
	ds_read_b32 v206, v6 offset:32
	ds_read_b32 v207, v6 offset:48
	ds_read_b32 v208, v6 offset:64
	ds_read_b32 v209, v6 offset:80
	ds_read_b32 v210, v6 offset:96
	ds_read_b32 v211, v6 offset:112
	ds_read_b32 v212, v6 offset:128
	ds_read_b32 v213, v6 offset:144
	ds_read_b32 v214, v6 offset:160
	ds_read_b32 v215, v6 offset:176
	ds_read_b32 v216, v6 offset:192
	ds_read_b32 v217, v6 offset:208
	ds_read_b32 v218, v6 offset:224
	ds_read_b32 v219, v6 offset:240
	ds_read_b32 v220, v4 offset:0
	ds_read_b32 v221, v4 offset:1088
	ds_read_b32 v222, v4 offset:2176
	ds_read_b32 v223, v4 offset:3264
	ds_read_b32 v224, v4 offset:4352
	ds_read_b32 v225, v4 offset:5440
	ds_read_b32 v226, v4 offset:6528
	ds_read_b32 v227, v4 offset:7616
	ds_read_b32 v228, v4 offset:8704
	ds_read_b32 v229, v4 offset:9792
	ds_read_b32 v230, v4 offset:10880
	ds_read_b32 v231, v4 offset:11968
	ds_read_b32 v232, v4 offset:13056
	ds_read_b32 v233, v4 offset:14144
	ds_read_b32 v234, v4 offset:15232
	ds_read_b32 v235, v4 offset:16320
	s_waitcnt lgkmcnt(0)
	v_mul_f32_e32 v204, 0x3fb8aa3b, v204
	v_mul_f32_e32 v205, 0x3fb8aa3b, v205
	v_mul_f32_e32 v206, 0x3fb8aa3b, v206
	v_mul_f32_e32 v207, 0x3fb8aa3b, v207
	v_mul_f32_e32 v208, 0x3fb8aa3b, v208
	v_mul_f32_e32 v209, 0x3fb8aa3b, v209
	v_mul_f32_e32 v210, 0x3fb8aa3b, v210
	v_mul_f32_e32 v211, 0x3fb8aa3b, v211
	v_mul_f32_e32 v212, 0x3fb8aa3b, v212
	v_mul_f32_e32 v213, 0x3fb8aa3b, v213
	v_mul_f32_e32 v214, 0x3fb8aa3b, v214
	v_mul_f32_e32 v215, 0x3fb8aa3b, v215
	v_mul_f32_e32 v216, 0x3fb8aa3b, v216
	v_mul_f32_e32 v217, 0x3fb8aa3b, v217
	v_mul_f32_e32 v218, 0x3fb8aa3b, v218
	v_mul_f32_e32 v219, 0x3fb8aa3b, v219
	v_exp_f32_e32 v204, v204
	v_exp_f32_e32 v205, v205
	v_exp_f32_e32 v206, v206
	v_exp_f32_e32 v207, v207
	v_exp_f32_e32 v208, v208
	v_exp_f32_e32 v209, v209
	v_exp_f32_e32 v210, v210
	v_exp_f32_e32 v211, v211
	v_exp_f32_e32 v212, v212
	v_exp_f32_e32 v213, v213
	v_exp_f32_e32 v214, v214
	v_exp_f32_e32 v215, v215
	v_exp_f32_e32 v216, v216
	v_exp_f32_e32 v217, v217
	v_exp_f32_e32 v218, v218
	v_exp_f32_e32 v219, v219
	v_mul_f32_e32 v8, v8, v220
	v_mul_f32_e32 v9, v9, v221
	v_mul_f32_e32 v10, v10, v222
	v_mul_f32_e32 v11, v11, v223
	v_mul_f32_e32 v12, v12, v224
	v_mul_f32_e32 v13, v13, v225
	v_mul_f32_e32 v14, v14, v226
	v_mul_f32_e32 v15, v15, v227
	v_mul_f32_e32 v16, v16, v228
	v_mul_f32_e32 v17, v17, v229
	v_mul_f32_e32 v18, v18, v230
	v_mul_f32_e32 v19, v19, v231
	v_mul_f32_e32 v20, v20, v232
	v_mul_f32_e32 v21, v21, v233
	v_mul_f32_e32 v22, v22, v234
	v_mul_f32_e32 v23, v23, v235
	v_mul_f32_e32 v8, v8, v204
	v_mul_f32_e32 v9, v9, v205
	v_mul_f32_e32 v10, v10, v206
	v_mul_f32_e32 v11, v11, v207
	v_mul_f32_e32 v12, v12, v208
	v_mul_f32_e32 v13, v13, v209
	v_mul_f32_e32 v14, v14, v210
	v_mul_f32_e32 v15, v15, v211
	v_mul_f32_e32 v16, v16, v212
	v_mul_f32_e32 v17, v17, v213
	v_mul_f32_e32 v18, v18, v214
	v_mul_f32_e32 v19, v19, v215
	v_mul_f32_e32 v20, v20, v216
	v_mul_f32_e32 v21, v21, v217
	v_mul_f32_e32 v22, v22, v218
	v_mul_f32_e32 v23, v23, v219

; DI float fexp2(float x) { return __builtin_amdgcn_exp2f(x); }
;     ...
;     for (int e = tid; e < 8192; e += 512) { const int i = e >> 7, cc = e & 127; const float bi = bet[i];
;         rhs[i * 132 + cc] = cc < 64 ? vc[i * 68 + cc] * bi : kc[i * 68 + cc - 64] * bi * fexp2(gcs[i] * 1.4426950408889634f); }
.Lrhs_w_1:
	s_mov_b64 exec, s[52:53]
	ds_write_b32 v5, v8 offset:0
	ds_write_b32 v5, v9 offset:2112
	ds_write_b32 v5, v10 offset:4224
	ds_write_b32 v5, v11 offset:6336
	ds_write_b32 v5, v12 offset:8448
	ds_write_b32 v5, v13 offset:10560
	ds_write_b32 v5, v14 offset:12672
	ds_write_b32 v5, v15 offset:14784
	ds_write_b32 v5, v16 offset:16896
	ds_write_b32 v5, v17 offset:19008
	ds_write_b32 v5, v18 offset:21120
	ds_write_b32 v5, v19 offset:23232
	ds_write_b32 v5, v20 offset:25344
	ds_write_b32 v5, v21 offset:27456
	ds_write_b32 v5, v22 offset:29568
	ds_write_b32 v5, v23 offset:31680
	s_mov_b64 s[26:27], 0
	s_ashr_i32 s69, s68, 31

; DI unsigned pk2(float lo, float hi) { typedef __bf16 b2 __attribute__((ext_vector_type(2))); f32x2 v = {lo, hi}; b2 b = __builtin_convertvector(v, b2); return __builtin_bit_cast(unsigned, b); }
; DI void cvt_phase(const Ctx& c, const float* src, bf16_t* dst, float* copy, size_t n) {
;     const size_t n4 = n / 4, stride = (size_t)c.G * 512;
;     for (size_t i = (size_t)c.bid * 512 + c.tid; i < n4; i += stride) { const f32x4 v = ((const f32x4*)src)[i]; u32x2 w; w.x = pk2(v[0], v[1]); w.y = pk2(v[2], v[3]); ((u32x2*)dst)[i] = w; if (copy) ((f32x4*)copy)[i] = v; }
; }
;     ...
;     else if constexpr (SP == 7) { pg8::Gemm g{AB, W + OW_O, T_, 1024, 1024, NINP}; pg8::StaticOrder S; S.init(T_, 1024, c.G, c.bid);
;         pg8::EpiResidLn E{H, H, HB0, DM, ALPHA, 1.0f, ln_g + DM, ln_b + DM, (unsigned long long*)(ws + WS_CTL + 524288), (unsigned*)(ws + WS_CTL + 131072) + (l * 3 + 1) * 4096};
;         pg8::gemm_phase<pg8::EpiResidLn, pg8::StaticOrder, false>(c.lds, g, S, E);
;         cvt_phase(c, args.in[1] + (size_t)l * T_ * 256, (bf16_t*)(ws + WS_SVT), nullptr, (size_t)T_ * 256); }
.LBB0_2356:
	s_lshl_b64 s[0:1], s[70:71], 9
	v_mov_b32_e32 v153, 0
	s_waitcnt vmcnt(0)
	v_lshl_add_u64 v[0:1], s[0:1], 0, v[152:153]
	s_mov_b64 s[0:1], 0x100000
	v_cmp_gt_u64_e32 vcc, s[0:1], v[0:1]
	s_and_saveexec_b64 s[0:1], vcc
	s_cbranch_execz .LBB0_2359
	s_lshl_b64 s[4:5], s[2:3], 9
	s_lshl_b64 s[6:7], s[70:71], 13
	s_add_u32 s6, s38, s6
	v_lshlrev_b32_e32 v2, 4, v152
	v_mov_b32_e32 v3, v153
	s_addc_u32 s7, s39, s7
	v_lshl_add_u64 v[2:3], s[6:7], 0, v[2:3]
	s_mov_b64 s[6:7], 0x1000000
	v_lshl_add_u64 v[2:3], v[2:3], 0, s[6:7]
	s_lshl_b64 s[6:7], s[2:3], 13
	s_lshl_b64 s[8:9], s[70:71], 12
	s_add_u32 s8, s34, s8
	v_lshlrev_b32_e32 v4, 3, v152
	v_mov_b32_e32 v5, v153
	s_addc_u32 s9, s35, s9
	v_lshl_add_u64 v[4:5], s[8:9], 0, v[4:5]
	s_mov_b64 s[8:9], 0x10800000
	v_lshl_add_u64 v[4:5], v[4:5], 0, s[8:9]
	s_lshl_b64 s[2:3], s[2:3], 12
	s_mov_b64 s[8:9], 0
	s_mov_b64 s[10:11], 0xfffff
	s_cmp_lg_u32 s4, 0x20000
	s_cbranch_scc1 .LBB0_2358
	s_movk_i32 s101, 1
.Lcvt_fast_2:
	global_load_dwordx4 v[8:11], v[2:3], off
	v_lshl_add_u64 v[2:3], v[2:3], 0, s[6:7]
	global_load_dwordx4 v[12:15], v[2:3], off
	v_lshl_add_u64 v[2:3], v[2:3], 0, s[6:7]
	global_load_dwordx4 v[16:19], v[2:3], off
	v_lshl_add_u64 v[2:3], v[2:3], 0, s[6:7]
	global_load_dwordx4 v[20:23], v[2:3], off
	v_lshl_add_u64 v[2:3], v[2:3], 0, s[6:7]
	global_load_dwordx4 v[24:27], v[2:3], off
	v_lshl_add_u64 v[2:3], v[2:3], 0, s[6:7]
	global_load_dwordx4 v[28:31], v[2:3], off
	v_lshl_add_u64 v[2:3], v[2:3], 0, s[6:7]
	global_load_dwordx4 v[32:35], v[2:3], off
	v_lshl_add_u64 v[2:3], v[2:3], 0, s[6:7]
	global_load_dwordx4 v[36:39], v[2:3], off
	v_lshl_add_u64 v[2:3], v[2:3], 0, s[6:7]
	s_waitcnt vmcnt(7)
	v_cvt_pk_bf16_f32 v8, v8, v9
	v_cvt_pk_bf16_f32 v9, v10, v11
	global_store_dwordx2 v[4:5], v[8:9], off
	v_lshl_add_u64 v[4:5], v[4:5], 0, s[2:3]
	s_waitcnt vmcnt(7)
	v_cvt_pk_bf16_f32 v12, v12, v13
	v_cvt_pk_bf16_f32 v13, v14, v15
	global_store_dwordx2 v[4:5], v[12:13], off
	v_lshl_add_u64 v[4:5], v[4:5], 0, s[2:3]
	s_waitcnt vmcnt(7)
	v_cvt_pk_bf16_f32 v16, v16, v17
	v_cvt_pk_bf16_f32 v17, v18, v19
	global_store_dwordx2 v[4:5], v[16:17], off
	v_lshl_add_u64 v[4:5], v[4:5], 0, s[2:3]
	s_waitcnt vmcnt(7)
	v_cvt_pk_bf16_f32 v20, v20, v21
	v_cvt_pk_bf16_f32 v21, v22, v23
	global_store_dwordx2 v[4:5], v[20:21], off
	v_lshl_add_u64 v[4:5], v[4:5], 0, s[2:3]
	s_waitcnt vmcnt(7)
	v_cvt_pk_bf16_f32 v24, v24, v25
	v_cvt_pk_bf16_f32 v25, v26, v27
	global_store_dwordx2 v[4:5], v[24:25], off
	v_lshl_add_u64 v[4:5], v[4:5], 0, s[2:3]
	s_waitcnt vmcnt(7)
	v_cvt_pk_bf16_f32 v28, v28, v29
	v_cvt_pk_bf16_f32 v29, v30, v31
	global_store_dwordx2 v[4:5], v[28:29], off
	v_lshl_add_u64 v[4:5], v[4:5], 0, s[2:3]
	s_waitcnt vmcnt(7)
	v_cvt_pk_bf16_f32 v32, v32, v33
	v_cvt_pk_bf16_f32 v33, v34, v35
	global_store_dwordx2 v[4:5], v[32:33], off
	v_lshl_add_u64 v[4:5], v[4:5], 0, s[2:3]
	s_waitcnt vmcnt(7)
	v_cvt_pk_bf16_f32 v36, v36, v37
	v_cvt_pk_bf16_f32 v37, v38, v39
	global_store_dwordx2 v[4:5], v[36:37], off
	v_lshl_add_u64 v[4:5], v[4:5], 0, s[2:3]
	s_sub_u32 s101, s101, 1
	s_cmp_lg_u32 s101, 0
	s_cbranch_scc1 .Lcvt_fast_2
	s_branch .LBB0_2359
